# in-proj tail round: each of the 16 tail tiles per XCD split into two 128-row half tiles run by WGs lb and lb+16 (own 8-load prologue/loop, half the MFMA groups, half the epilogue stores)
# speedup vs baseline: 1.0049x; 1.0049x over previous
; __global__ void __launch_bounds__(256, 2) hymba_mega(Params p) {
;     ...
;   for (int layer = 0; layer < DEPTH; ++layer) {
;     for (int rep = 0; rep < REP_G0; ++rep) {
;       for (int u = lb; u < 8 * 26; u += nxb) gemm_tile<0>(p, layer, xcd + 8 * (u & 7), u >> 3, sm, wv);
.LBB0_109:
	s_mov_b32 s40, 0
	v_readlane_b32 s0, v250, 1
	v_readlane_b32 s1, v250, 2
	s_mov_b64 s[44:45], s[20:21]
	s_andn2_b64 vcc, exec, s[0:1]
	s_cbranch_vccnz .LBB0_141
	v_readlane_b32 s2, v250, 26
	s_mul_i32 s0, s2, 0x680000
	v_readlane_b32 s3, v250, 27
	s_add_u32 s16, s56, s0
	s_mov_b32 s0, s2
	s_mov_b32 s3, s25
	v_writelane_b32 v250, s0, 26
	s_addc_u32 s17, s57, 0
	s_nop 0
	v_writelane_b32 v250, s1, 27
	s_lshl_b64 s[0:1], s[2:3], 16
	s_add_u32 s0, s92, s0
	s_addc_u32 s1, s93, s1
	v_readlane_b32 s18, v250, 23
	s_branch .LBB0_113

; template <bool VT>
; DI void gemm_mainloop(f32x4 (&acc)[8][4], const char* abase, const char* bbase, unsigned toff, u16* sA, u16* sB, int loff, int wm, int wn, int fr, int fq) {
;   const __amdgpu_buffer_rsrc_t ra_rs = __builtin_amdgcn_make_buffer_rsrc((void*)abase, (short)0, 256 * 2048, 0x00020000);
;   const __amdgpu_buffer_rsrc_t rb_rs = __builtin_amdgcn_make_buffer_rsrc((void*)bbase, (short)0, 128 * 2048, 0x00020000);
;   u32x4 ra[8], rb[4];
; #pragma unroll
;   for (int i = 0; i < 8; ++i) ra[i] = __builtin_amdgcn_raw_buffer_load_b128(ra_rs, (int)toff, i * 65536, 0);
; #pragma unroll
;   for (int i = 0; i < 4; ++i) rb[i] = __builtin_amdgcn_raw_buffer_load_b128(rb_rs, (int)toff, i * 65536, 0);
; template <int EPI>
; DI void gemm_tile(const Params& p, int layer, int mt, int nt, u16* sm, int wv) {
;   const int tid = tid_now(wv), w = tid >> 6;
;   int lane = tid & 63, fr = lane & 15, fq = lane >> 4;
;   const u16* A = (EPI == 0) ? p.xg : p.y;
;   const u16* Bt = (EPI == 0) ? p.wtin + (size_t)layer * DIN * 1024 : p.wtout + (size_t)layer * 1024 * 1024;
;   const int m0 = mt * 256, n0 = nt * 128;
;   const char* abase = (const char*)(A + (size_t)m0 * 1024);
;   const char* bbase = (const char*)(Bt + (size_t)n0 * 1024);
;   const unsigned toff = (unsigned)(tid >> 3) * 2048u + (unsigned)(tid & 7) * 16u;
;   const int loff = (tid >> 3) * GSTR + (tid & 7) * 8;
;   u16* sA = sm;
;   u16* sB = sm + 256 * GSTR;
;   f32x4 acc[8][4];
; #pragma unroll
;   for (int i = 0; i < 8; ++i)
; #pragma unroll
;     for (int j = 0; j < 4; ++j)
; #pragma unroll
;       for (int e = 0; e < 4; ++e) acc[i][j][e] = 0.f;
;   bool vtile = false;
;   if (EPI == 0) vtile = (nt == 4 || nt == 5 || nt == 13 || nt == 22 || nt == 23);
;   int wm = w >> 1, wn = w & 1;
;   if (EPI == 0 && vtile) { asm volatile("; v-tile main loop" ::: "memory"); gemm_mainloop<true>(acc, abase, bbase, toff, sA, sB, loff, wm, wn, fr, fq); }
;   else { asm volatile("; main loop" ::: "memory"); gemm_mainloop<false>(acc, abase, bbase, toff, sA, sB, loff, wm, wn, fr, fq); }
.LBB0_112:
	ds_read_b128 v[2:5], v140
	s_add_i32 s18, s18, s97
	v_lshl_add_u64 v[6:7], v[0:1], 1, v[132:133]
	s_cmpk_gt_i32 s18, 0xbf
	s_waitcnt lgkmcnt(0)
	global_store_dwordx4 v[6:7], v[2:5], off
	s_cbranch_scc1 .Lgx_exit
.LBB0_113:
	s_lshl_b32 s2, s18, 3
	s_ashr_i32 s20, s18, 3
	s_and_b32 s19, s2, 56
	s_lshl_b32 s2, s20, 7
	s_or_b32 s21, s19, s22
	s_ashr_i32 s3, s2, 31
	s_lshl_b64 s[4:5], s[2:3], 11
	s_lshl_b32 s6, s21, 19
	s_add_u32 s64, s60, s6
	s_addc_u32 s38, s61, 0
	s_add_u32 s84, s16, s4
	s_addc_u32 s39, s17, s5
	s_cmp_gt_u32 s20, 23
	s_cselect_b64 s[4:5], -1, 0
	s_lshr_b32 s6, 0xc02030, s20
	v_mbcnt_lo_u32_b32 v2, -1, 0
	v_mbcnt_hi_u32_b32 v2, -1, v2
	s_bitcmp1_b32 s6, 0
	v_add_u32_e32 v3, s33, v2
	v_and_b32_e32 v5, 7, v2
	v_ashrrev_i32_e32 v4, 3, v3
	v_lshlrev_b32_e32 v0, 4, v5
	s_cselect_b64 s[36:37], -1, 0
	v_lshl_or_b32 v0, v4, 11, v0
	v_mul_lo_u32 v4, v4, s24
	s_xor_b64 s[36:37], s[36:37], -1
	v_and_b32_e32 v6, 15, v2
	v_bfe_u32 v2, v2, 4, 2
	v_lshl_add_u32 v4, v5, 3, v4
	s_or_b64 s[4:5], s[4:5], s[36:37]
	v_bfe_u32 v5, v3, 6, 1
	s_mov_b32 s36, 0x7ffff80
	v_lshlrev_b32_e32 v180, 1, v4
	v_lshl_or_b32 v4, v5, 6, v6
	v_lshlrev_b32_e32 v181, 4, v2
	v_and_or_b32 v2, v3, s36, v6
	s_movk_i32 s36, 0xa0
	s_mov_b64 s[6:7], -1
	s_and_b32 s65, s38, 0xffff
	s_and_b32 s85, s39, 0xffff
	s_and_b64 vcc, exec, s[4:5]
	v_mul_u32_u24_e32 v182, 0xa0, v4
	v_mul_lo_u32 v183, v2, s36
	s_cbranch_vccz .LBB0_119
	s_cmp_eq_u32 s40, 1
	s_cbranch_scc1 .Lh0_pro
	s_cmp_eq_u32 s40, 2
	s_cbranch_scc1 .Lh1_pro
	s_mov_b32 s36, 0x50000
	buffer_load_dwordx4 v[130:133], v0, s[64:67], 0 offen
	buffer_load_dwordx4 v[134:137], v0, s[64:67], s67 offen
	s_mov_b32 s6, 0x10000
	s_mov_b32 s7, 0x30000
	buffer_load_dwordx4 v[150:153], v0, s[64:67], s36 offen
	s_mov_b32 s36, 0x60000
	buffer_load_dwordx4 v[138:141], v0, s[64:67], s6 offen
	buffer_load_dwordx4 v[142:145], v0, s[64:67], s7 offen
	buffer_load_dwordx4 v[154:157], v0, s[64:67], s36 offen
	buffer_load_dwordx4 v[146:149], v0, s[64:67], s86 offen
	s_mov_b32 s36, 0x70000
	s_mov_b32 s87, s67
	buffer_load_dwordx4 v[158:161], v0, s[64:67], s36 offen
	buffer_load_dwordx4 v[162:165], v0, s[84:87], 0 offen
	buffer_load_dwordx4 v[166:169], v0, s[84:87], s67 offen
	buffer_load_dwordx4 v[170:173], v0, s[84:87], s6 offen
	buffer_load_dwordx4 v[174:177], v0, s[84:87], s7 offen
	v_mov_b32_e32 v10, 0
	s_mov_b32 s6, 0x70080
	v_add_u32_e32 v184, v181, v182
	v_add_u32_e32 v185, v181, v183
	v_mov_b32_e32 v11, v10
	v_mov_b32_e32 v12, v10
	v_mov_b32_e32 v13, v10
	v_mov_b32_e32 v2, v10
	v_mov_b32_e32 v3, v10
	v_mov_b32_e32 v4, v10
	v_mov_b32_e32 v5, v10
	v_mov_b32_e32 v6, v10
	v_mov_b32_e32 v7, v10
	v_mov_b32_e32 v8, v10
	v_mov_b32_e32 v9, v10
	v_mov_b32_e32 v14, v10
	v_mov_b32_e32 v15, v10
	v_mov_b32_e32 v16, v10
	v_mov_b32_e32 v17, v10
	v_mov_b32_e32 v18, v10
	v_mov_b32_e32 v19, v10
	v_mov_b32_e32 v20, v10
	v_mov_b32_e32 v21, v10
	v_mov_b32_e32 v22, v10
	v_mov_b32_e32 v23, v10
	v_mov_b32_e32 v24, v10
	v_mov_b32_e32 v25, v10
	v_mov_b32_e32 v26, v10
	v_mov_b32_e32 v27, v10
	v_mov_b32_e32 v28, v10
	v_mov_b32_e32 v29, v10
	v_mov_b32_e32 v30, v10
	v_mov_b32_e32 v31, v10
	v_mov_b32_e32 v32, v10
	v_mov_b32_e32 v33, v10
	v_mov_b32_e32 v34, v10
	v_mov_b32_e32 v35, v10
	v_mov_b32_e32 v36, v10
	v_mov_b32_e32 v37, v10
	v_mov_b32_e32 v38, v10
	v_mov_b32_e32 v39, v10
	v_mov_b32_e32 v40, v10
	v_mov_b32_e32 v41, v10
	v_mov_b32_e32 v42, v10
	v_mov_b32_e32 v43, v10
	v_mov_b32_e32 v44, v10
	v_mov_b32_e32 v45, v10
	v_mov_b32_e32 v46, v10
	v_mov_b32_e32 v47, v10
	v_mov_b32_e32 v48, v10
	v_mov_b32_e32 v49, v10
	v_mov_b32_e32 v50, v10
	v_mov_b32_e32 v51, v10
	v_mov_b32_e32 v52, v10
	v_mov_b32_e32 v53, v10
	v_mov_b32_e32 v54, v10
	v_mov_b32_e32 v55, v10
	v_mov_b32_e32 v56, v10
	v_mov_b32_e32 v57, v10
	v_mov_b32_e32 v58, v10
	v_mov_b32_e32 v59, v10
	v_mov_b32_e32 v60, v10
	v_mov_b32_e32 v61, v10
	v_mov_b32_e32 v62, v10
	v_mov_b32_e32 v63, v10
	v_mov_b32_e32 v64, v10
	v_mov_b32_e32 v65, v10
	v_mov_b32_e32 v66, v10
	v_mov_b32_e32 v67, v10
	v_mov_b32_e32 v68, v10
	v_mov_b32_e32 v69, v10
	s_waitcnt vmcnt(12)
	v_mov_b32_e32 v70, v10
	v_mov_b32_e32 v71, v10
	v_mov_b32_e32 v72, v10
	v_mov_b32_e32 v73, v10
	v_mov_b32_e32 v74, v10
	v_mov_b32_e32 v75, v10
	v_mov_b32_e32 v76, v10
	v_mov_b32_e32 v77, v10
	v_mov_b32_e32 v78, v10
	v_mov_b32_e32 v79, v10
	v_mov_b32_e32 v80, v10
	v_mov_b32_e32 v81, v10
	v_mov_b32_e32 v82, v10
	v_mov_b32_e32 v83, v10
	v_mov_b32_e32 v84, v10
	v_mov_b32_e32 v85, v10
	v_mov_b32_e32 v86, v10
	v_mov_b32_e32 v87, v10
	v_mov_b32_e32 v88, v10
	v_mov_b32_e32 v89, v10
	v_mov_b32_e32 v90, v10
	v_mov_b32_e32 v91, v10
	v_mov_b32_e32 v92, v10
	v_mov_b32_e32 v93, v10
	v_mov_b32_e32 v94, v10
	v_mov_b32_e32 v95, v10
	v_mov_b32_e32 v96, v10
	v_mov_b32_e32 v97, v10
	v_mov_b32_e32 v98, v10
	v_mov_b32_e32 v99, v10
	v_mov_b32_e32 v100, v10
	v_mov_b32_e32 v101, v10
	v_mov_b32_e32 v102, v10
	v_mov_b32_e32 v103, v10
	v_mov_b32_e32 v104, v10
	v_mov_b32_e32 v105, v10
	v_mov_b32_e32 v106, v10
	v_mov_b32_e32 v107, v10
	v_mov_b32_e32 v108, v10
	v_mov_b32_e32 v109, v10
	v_mov_b32_e32 v110, v10
	v_mov_b32_e32 v111, v10
	v_mov_b32_e32 v112, v10
	v_mov_b32_e32 v113, v10
	v_mov_b32_e32 v114, v10
	v_mov_b32_e32 v115, v10
	v_mov_b32_e32 v116, v10
	v_mov_b32_e32 v117, v10
	v_mov_b32_e32 v118, v10
	v_mov_b32_e32 v119, v10
	v_mov_b32_e32 v120, v10
	v_mov_b32_e32 v121, v10
	v_mov_b32_e32 v122, v10
	v_mov_b32_e32 v123, v10
	v_mov_b32_e32 v124, v10
	v_mov_b32_e32 v125, v10
	v_mov_b32_e32 v126, v10
	v_mov_b32_e32 v127, v10
	v_mov_b32_e32 v128, v10
	v_mov_b32_e32 v129, v10
	s_branch .LBB0_116

; DI f32x4 mfma16(bf16x8 a, bf16x8 b, f32x4 c) { return __builtin_amdgcn_mfma_f32_16x16x32_bf16(a, b, c, 0, 0, 0); }
; template <bool VT>
; DI void gemm_kslab(f32x4 (&acc)[8][4], const u16* sA, const u16* sB, int wm, int wn, int fr, int fq) {
; #pragma unroll
;   for (int ks = 0; ks < 2; ++ks) {
;     bf16x8 tb[4], ta[8];
; #pragma unroll
;     for (int j = 0; j < 4; ++j) tb[j] = ldsv(sB + (wn * 64 + 16 * j + fr) * GSTR + ks * 32 + 8 * fq);
; #pragma unroll
;     for (int i = 0; i < 8; ++i) ta[i] = ldsv(sA + (wm * 128 + 16 * i + fr) * GSTR + ks * 32 + 8 * fq);
; #pragma unroll
;     for (int i = 0; i < 8; ++i)
; #pragma unroll
;       for (int j = 0; j < 4; ++j)
;         acc[i][j] = VT ? mfma16(ta[i], tb[j], acc[i][j]) : mfma16(tb[j], ta[i], acc[i][j]);
;   }
; template <bool VT>
; DI void gemm_mainloop(f32x4 (&acc)[8][4], const char* abase, const char* bbase, unsigned toff, u16* sA, u16* sB, int loff, int wm, int wn, int fr, int fq) {
;   const __amdgpu_buffer_rsrc_t ra_rs = __builtin_amdgcn_make_buffer_rsrc((void*)abase, (short)0, 256 * 2048, 0x00020000);
;   const __amdgpu_buffer_rsrc_t rb_rs = __builtin_amdgcn_make_buffer_rsrc((void*)bbase, (short)0, 128 * 2048, 0x00020000);
;   u32x4 ra[8], rb[4];
; #pragma unroll
;   for (int i = 0; i < 8; ++i) ra[i] = __builtin_amdgcn_raw_buffer_load_b128(ra_rs, (int)toff, i * 65536, 0);
; #pragma unroll
;   for (int i = 0; i < 4; ++i) rb[i] = __builtin_amdgcn_raw_buffer_load_b128(rb_rs, (int)toff, i * 65536, 0);
.Lh0_pro:
	s_mov_b32 s6, 0x10000
	s_mov_b32 s7, 0x30000
	s_mov_b32 s87, s67
	s_mov_b32 s36, 0x50000
	buffer_load_dwordx4 v[146:149], v0, s[64:67], s86 offen
	buffer_load_dwordx4 v[150:153], v0, s[64:67], s36 offen
	buffer_load_dwordx4 v[130:133], v0, s[64:67], 0 offen
	buffer_load_dwordx4 v[138:141], v0, s[64:67], s6 offen
	buffer_load_dwordx4 v[162:165], v0, s[84:87], 0 offen
	buffer_load_dwordx4 v[170:173], v0, s[84:87], s6 offen
	buffer_load_dwordx4 v[166:169], v0, s[84:87], s67 offen
	buffer_load_dwordx4 v[174:177], v0, s[84:87], s7 offen
	v_mov_b32_e32 v10, 0
	s_mov_b32 s6, 0x70080
	v_add_u32_e32 v184, v181, v182
	v_add_u32_e32 v185, v181, v183
	v_mov_b32_e32 v11, v10
	v_mov_b32_e32 v12, v10
	v_mov_b32_e32 v13, v10
	v_mov_b32_e32 v2, v10
	v_mov_b32_e32 v3, v10
	v_mov_b32_e32 v4, v10
	v_mov_b32_e32 v5, v10
	v_mov_b32_e32 v6, v10
	v_mov_b32_e32 v7, v10
	v_mov_b32_e32 v8, v10
	v_mov_b32_e32 v9, v10
	v_mov_b32_e32 v14, v10
	v_mov_b32_e32 v15, v10
	v_mov_b32_e32 v16, v10
	v_mov_b32_e32 v17, v10
	v_mov_b32_e32 v18, v10
	v_mov_b32_e32 v19, v10
	v_mov_b32_e32 v20, v10
	v_mov_b32_e32 v21, v10
	v_mov_b32_e32 v22, v10
	v_mov_b32_e32 v23, v10
	v_mov_b32_e32 v24, v10
	v_mov_b32_e32 v25, v10
	v_mov_b32_e32 v26, v10
	v_mov_b32_e32 v27, v10
	v_mov_b32_e32 v28, v10
	v_mov_b32_e32 v29, v10
	v_mov_b32_e32 v30, v10
	v_mov_b32_e32 v31, v10
	v_mov_b32_e32 v32, v10
	v_mov_b32_e32 v33, v10
	v_mov_b32_e32 v34, v10
	v_mov_b32_e32 v35, v10
	v_mov_b32_e32 v36, v10
	v_mov_b32_e32 v37, v10
	v_mov_b32_e32 v38, v10
	v_mov_b32_e32 v39, v10
	v_mov_b32_e32 v40, v10
	v_mov_b32_e32 v41, v10
	v_mov_b32_e32 v42, v10
	v_mov_b32_e32 v43, v10
	v_mov_b32_e32 v44, v10
	v_mov_b32_e32 v45, v10
	v_mov_b32_e32 v46, v10
	v_mov_b32_e32 v47, v10
	v_mov_b32_e32 v48, v10
	v_mov_b32_e32 v49, v10
	v_mov_b32_e32 v50, v10
	v_mov_b32_e32 v51, v10
	v_mov_b32_e32 v52, v10
	v_mov_b32_e32 v53, v10
	v_mov_b32_e32 v54, v10
	v_mov_b32_e32 v55, v10
	v_mov_b32_e32 v56, v10
	v_mov_b32_e32 v57, v10
	v_mov_b32_e32 v58, v10
	v_mov_b32_e32 v59, v10
	v_mov_b32_e32 v60, v10
	v_mov_b32_e32 v61, v10
	v_mov_b32_e32 v62, v10
	v_mov_b32_e32 v63, v10
	v_mov_b32_e32 v64, v10
	v_mov_b32_e32 v65, v10
	v_mov_b32_e32 v66, v10
	v_mov_b32_e32 v67, v10
	v_mov_b32_e32 v68, v10
	v_mov_b32_e32 v69, v10
	s_waitcnt vmcnt(8)
	v_mov_b32_e32 v70, v10
	v_mov_b32_e32 v71, v10
	v_mov_b32_e32 v72, v10
	v_mov_b32_e32 v73, v10
	v_mov_b32_e32 v74, v10
	v_mov_b32_e32 v75, v10
	v_mov_b32_e32 v76, v10
	v_mov_b32_e32 v77, v10
	v_mov_b32_e32 v78, v10
	v_mov_b32_e32 v79, v10
	v_mov_b32_e32 v80, v10
	v_mov_b32_e32 v81, v10
	v_mov_b32_e32 v82, v10
	v_mov_b32_e32 v83, v10
	v_mov_b32_e32 v84, v10
	v_mov_b32_e32 v85, v10
	v_mov_b32_e32 v86, v10
	v_mov_b32_e32 v87, v10
	v_mov_b32_e32 v88, v10
	v_mov_b32_e32 v89, v10
	v_mov_b32_e32 v90, v10
	v_mov_b32_e32 v91, v10
	v_mov_b32_e32 v92, v10
	v_mov_b32_e32 v93, v10
	v_mov_b32_e32 v94, v10
	v_mov_b32_e32 v95, v10
	v_mov_b32_e32 v96, v10
	v_mov_b32_e32 v97, v10
	v_mov_b32_e32 v98, v10
	v_mov_b32_e32 v99, v10
	v_mov_b32_e32 v100, v10
	v_mov_b32_e32 v101, v10
	v_mov_b32_e32 v102, v10
	v_mov_b32_e32 v103, v10
	v_mov_b32_e32 v104, v10
	v_mov_b32_e32 v105, v10
	v_mov_b32_e32 v106, v10
	v_mov_b32_e32 v107, v10
	v_mov_b32_e32 v108, v10
	v_mov_b32_e32 v109, v10
	v_mov_b32_e32 v110, v10
	v_mov_b32_e32 v111, v10
	v_mov_b32_e32 v112, v10
	v_mov_b32_e32 v113, v10
	v_mov_b32_e32 v114, v10
	v_mov_b32_e32 v115, v10
	v_mov_b32_e32 v116, v10
	v_mov_b32_e32 v117, v10
	v_mov_b32_e32 v118, v10
	v_mov_b32_e32 v119, v10
	v_mov_b32_e32 v120, v10
	v_mov_b32_e32 v121, v10
	v_mov_b32_e32 v122, v10
	v_mov_b32_e32 v123, v10
	v_mov_b32_e32 v124, v10
	v_mov_b32_e32 v125, v10
	v_mov_b32_e32 v126, v10
	v_mov_b32_e32 v127, v10
	v_mov_b32_e32 v128, v10
	v_mov_b32_e32 v129, v10
	s_branch .Lh0_116
.Lh0_115:
	s_setprio 1
	ds_read_b128 v[202:205], v184 offset:40960
	ds_read_b128 v[206:209], v184 offset:43520
	ds_read_b128 v[214:217], v184 offset:46080
	ds_read_b128 v[218:221], v184 offset:48640
	ds_read_b128 v[210:213], v185
	ds_read_b128 v[222:225], v185 offset:2560
	s_waitcnt lgkmcnt(1)
	v_mfma_f32_16x16x32_bf16 v[126:129], v[202:205], v[210:213], v[126:129]
	v_mfma_f32_16x16x32_bf16 v[122:125], v[206:209], v[210:213], v[122:125]
	v_mfma_f32_16x16x32_bf16 v[118:121], v[214:217], v[210:213], v[118:121]
	v_mfma_f32_16x16x32_bf16 v[114:117], v[218:221], v[210:213], v[114:117]
	ds_read_b128 v[210:213], v185 offset:5120
	s_waitcnt lgkmcnt(1)
	v_mfma_f32_16x16x32_bf16 v[110:113], v[202:205], v[222:225], v[110:113]
	v_mfma_f32_16x16x32_bf16 v[106:109], v[206:209], v[222:225], v[106:109]
	v_mfma_f32_16x16x32_bf16 v[102:105], v[214:217], v[222:225], v[102:105]
	v_mfma_f32_16x16x32_bf16 v[98:101], v[218:221], v[222:225], v[98:101]
	ds_read_b128 v[222:225], v185 offset:7680
	ds_read_b128 v[226:229], v184 offset:41024
	ds_read_b128 v[230:233], v184 offset:43584
	ds_read_b128 v[234:237], v184 offset:46144
	ds_read_b128 v[238:241], v184 offset:48704
	ds_read_b128 v[242:245], v185 offset:64
	ds_read_b128 v[246:249], v185 offset:2624
	s_waitcnt lgkmcnt(7)
	v_mfma_f32_16x16x32_bf16 v[94:97], v[202:205], v[210:213], v[94:97]
	v_mfma_f32_16x16x32_bf16 v[90:93], v[206:209], v[210:213], v[90:93]
	v_mfma_f32_16x16x32_bf16 v[86:89], v[214:217], v[210:213], v[86:89]
	v_mfma_f32_16x16x32_bf16 v[82:85], v[218:221], v[210:213], v[82:85]
	s_waitcnt lgkmcnt(6)
	v_mfma_f32_16x16x32_bf16 v[78:81], v[202:205], v[222:225], v[78:81]
	v_mfma_f32_16x16x32_bf16 v[74:77], v[206:209], v[222:225], v[74:77]
	v_mfma_f32_16x16x32_bf16 v[70:73], v[214:217], v[222:225], v[70:73]
	v_mfma_f32_16x16x32_bf16 v[66:69], v[218:221], v[222:225], v[66:69]
	s_waitcnt lgkmcnt(1)
	v_mfma_f32_16x16x32_bf16 v[126:129], v[226:229], v[242:245], v[126:129]
	v_mfma_f32_16x16x32_bf16 v[122:125], v[230:233], v[242:245], v[122:125]
	v_mfma_f32_16x16x32_bf16 v[118:121], v[234:237], v[242:245], v[118:121]
	v_mfma_f32_16x16x32_bf16 v[114:117], v[238:241], v[242:245], v[114:117]
	ds_read_b128 v[202:205], v185 offset:5184
	s_waitcnt lgkmcnt(1)
	v_mfma_f32_16x16x32_bf16 v[110:113], v[226:229], v[246:249], v[110:113]
	v_mfma_f32_16x16x32_bf16 v[106:109], v[230:233], v[246:249], v[106:109]
	v_mfma_f32_16x16x32_bf16 v[102:105], v[234:237], v[246:249], v[102:105]
	v_mfma_f32_16x16x32_bf16 v[98:101], v[238:241], v[246:249], v[98:101]
	ds_read_b128 v[206:209], v185 offset:7744
	s_waitcnt lgkmcnt(1)
	v_mfma_f32_16x16x32_bf16 v[94:97], v[226:229], v[202:205], v[94:97]
	v_mfma_f32_16x16x32_bf16 v[90:93], v[230:233], v[202:205], v[90:93]
	v_mfma_f32_16x16x32_bf16 v[86:89], v[234:237], v[202:205], v[86:89]
	v_mfma_f32_16x16x32_bf16 v[82:85], v[238:241], v[202:205], v[82:85]
	s_waitcnt lgkmcnt(0)
	v_mfma_f32_16x16x32_bf16 v[78:81], v[226:229], v[206:209], v[78:81]
	v_mfma_f32_16x16x32_bf16 v[74:77], v[230:233], v[206:209], v[74:77]
	v_mfma_f32_16x16x32_bf16 v[70:73], v[234:237], v[206:209], v[70:73]
	v_mfma_f32_16x16x32_bf16 v[66:69], v[238:241], v[206:209], v[66:69]
	s_setprio 0
	s_addk_i32 s6, 0x80
	s_cmp_lg_u32 s6, 0x70880
	s_cbranch_scc0 .LBB0_118
; template <bool VT>
; DI void gemm_mainloop(f32x4 (&acc)[8][4], const char* abase, const char* bbase, unsigned toff, u16* sA, u16* sB, int loff, int wm, int wn, int fr, int fq) {
;   const __amdgpu_buffer_rsrc_t ra_rs = __builtin_amdgcn_make_buffer_rsrc((void*)abase, (short)0, 256 * 2048, 0x00020000);
;   const __amdgpu_buffer_rsrc_t rb_rs = __builtin_amdgcn_make_buffer_rsrc((void*)bbase, (short)0, 128 * 2048, 0x00020000);
;   u32x4 ra[8], rb[4];
; #pragma unroll
;   for (int i = 0; i < 8; ++i) ra[i] = __builtin_amdgcn_raw_buffer_load_b128(ra_rs, (int)toff, i * 65536, 0);
; #pragma unroll
;   for (int i = 0; i < 4; ++i) rb[i] = __builtin_amdgcn_raw_buffer_load_b128(rb_rs, (int)toff, i * 65536, 0);
; #pragma unroll 1
;   for (int kt = 0; kt < 16; ++kt) {
;     __syncthreads();
; #pragma unroll
;     for (int i = 0; i < 8; ++i) *(u32x4*)(sA + loff + i * 32 * GSTR) = ra[i];
; #pragma unroll
;     for (int i = 0; i < 4; ++i) *(u32x4*)(sB + loff + i * 32 * GSTR) = rb[i];
;     __syncthreads();
;     if (kt + 1 < 16) {
;       const int ko = (kt + 1) * 128;
; #pragma unroll
;       for (int i = 0; i < 8; ++i) ra[i] = __builtin_amdgcn_raw_buffer_load_b128(ra_rs, (int)toff, i * 65536 + ko, 0);
; #pragma unroll
;       for (int i = 0; i < 4; ++i) rb[i] = __builtin_amdgcn_raw_buffer_load_b128(rb_rs, (int)toff, i * 65536 + ko, 0);
;     }
.Lh0_116:
	s_cmp_eq_u32 s6, 0x70800
	s_barrier
	s_waitcnt vmcnt(5)
	ds_write_b128 v180, v[130:133]
	s_waitcnt vmcnt(4)
	ds_write_b128 v180, v[138:141] offset:5120
	ds_write_b128 v180, v[146:149] offset:20480
	ds_write_b128 v180, v[150:153] offset:25600
	s_waitcnt vmcnt(3)
	ds_write_b128 v180, v[162:165] offset:40960
	s_waitcnt vmcnt(2)
	ds_write_b128 v180, v[170:173] offset:46080
	s_waitcnt vmcnt(1)
	ds_write_b128 v180, v[166:169] offset:51200
	s_waitcnt vmcnt(0)
	ds_write_b128 v180, v[174:177] offset:56320
	s_waitcnt lgkmcnt(0)
	s_barrier
	s_cbranch_scc1 .Lh0_115
	s_add_i32 s7, s6, 0xfff90000
	s_add_i32 s36, s6, 0xfffa0000
	s_add_i32 s37, s6, 0xfffb0000
	s_add_i32 s38, s6, 0xfffc0000
	s_mov_b32 s87, s67
	s_add_i32 s39, s6, 0xfffd0000
	buffer_load_dwordx4 v[146:149], v0, s[64:67], s39 offen
	s_add_i32 s39, s6, 0xfffe0000
	buffer_load_dwordx4 v[150:153], v0, s[64:67], s39 offen
	buffer_load_dwordx4 v[130:133], v0, s[64:67], s7 offen
	buffer_load_dwordx4 v[138:141], v0, s[64:67], s36 offen
	buffer_load_dwordx4 v[162:165], v0, s[84:87], s7 offen
	buffer_load_dwordx4 v[170:173], v0, s[84:87], s36 offen
	buffer_load_dwordx4 v[166:169], v0, s[84:87], s37 offen
	buffer_load_dwordx4 v[174:177], v0, s[84:87], s38 offen
	s_branch .Lh0_115
.Lh1_pro:
	s_mov_b32 s6, 0x10000
	s_mov_b32 s7, 0x30000
	s_mov_b32 s87, s67
	s_mov_b32 s36, 0x60000
	s_mov_b32 s37, 0x70000
	buffer_load_dwordx4 v[134:137], v0, s[64:67], s67 offen
	buffer_load_dwordx4 v[142:145], v0, s[64:67], s7 offen
	buffer_load_dwordx4 v[154:157], v0, s[64:67], s36 offen
	buffer_load_dwordx4 v[158:161], v0, s[64:67], s37 offen
	buffer_load_dwordx4 v[162:165], v0, s[84:87], 0 offen
	buffer_load_dwordx4 v[170:173], v0, s[84:87], s6 offen
	buffer_load_dwordx4 v[166:169], v0, s[84:87], s67 offen
	buffer_load_dwordx4 v[174:177], v0, s[84:87], s7 offen
	v_mov_b32_e32 v10, 0
	s_mov_b32 s6, 0x70080
	v_add_u32_e32 v184, v181, v182
	v_add_u32_e32 v185, v181, v183
	v_mov_b32_e32 v11, v10
	v_mov_b32_e32 v12, v10
	v_mov_b32_e32 v13, v10
	v_mov_b32_e32 v2, v10
	v_mov_b32_e32 v3, v10
	v_mov_b32_e32 v4, v10
	v_mov_b32_e32 v5, v10
	v_mov_b32_e32 v6, v10
	v_mov_b32_e32 v7, v10
	v_mov_b32_e32 v8, v10
	v_mov_b32_e32 v9, v10
	v_mov_b32_e32 v14, v10
	v_mov_b32_e32 v15, v10
	v_mov_b32_e32 v16, v10
	v_mov_b32_e32 v17, v10
	v_mov_b32_e32 v18, v10
	v_mov_b32_e32 v19, v10
	v_mov_b32_e32 v20, v10
	v_mov_b32_e32 v21, v10
	v_mov_b32_e32 v22, v10
	v_mov_b32_e32 v23, v10
	v_mov_b32_e32 v24, v10
	v_mov_b32_e32 v25, v10
	v_mov_b32_e32 v26, v10
	v_mov_b32_e32 v27, v10
	v_mov_b32_e32 v28, v10
	v_mov_b32_e32 v29, v10
	v_mov_b32_e32 v30, v10
	v_mov_b32_e32 v31, v10
	v_mov_b32_e32 v32, v10
	v_mov_b32_e32 v33, v10
	v_mov_b32_e32 v34, v10
	v_mov_b32_e32 v35, v10
	v_mov_b32_e32 v36, v10
	v_mov_b32_e32 v37, v10
	v_mov_b32_e32 v38, v10
	v_mov_b32_e32 v39, v10
	v_mov_b32_e32 v40, v10
	v_mov_b32_e32 v41, v10
	v_mov_b32_e32 v42, v10
	v_mov_b32_e32 v43, v10
	v_mov_b32_e32 v44, v10
	v_mov_b32_e32 v45, v10
	v_mov_b32_e32 v46, v10
	v_mov_b32_e32 v47, v10
	v_mov_b32_e32 v48, v10
	v_mov_b32_e32 v49, v10
	v_mov_b32_e32 v50, v10
	v_mov_b32_e32 v51, v10
	v_mov_b32_e32 v52, v10
	v_mov_b32_e32 v53, v10
	v_mov_b32_e32 v54, v10
	v_mov_b32_e32 v55, v10
	v_mov_b32_e32 v56, v10
	v_mov_b32_e32 v57, v10
	v_mov_b32_e32 v58, v10
	v_mov_b32_e32 v59, v10
	v_mov_b32_e32 v60, v10
	v_mov_b32_e32 v61, v10
	v_mov_b32_e32 v62, v10
	v_mov_b32_e32 v63, v10
	v_mov_b32_e32 v64, v10
	v_mov_b32_e32 v65, v10
	v_mov_b32_e32 v66, v10
	v_mov_b32_e32 v67, v10
	v_mov_b32_e32 v68, v10
	v_mov_b32_e32 v69, v10
	s_waitcnt vmcnt(8)
	v_mov_b32_e32 v70, v10
	v_mov_b32_e32 v71, v10
	v_mov_b32_e32 v72, v10
	v_mov_b32_e32 v73, v10
	v_mov_b32_e32 v74, v10
	v_mov_b32_e32 v75, v10
	v_mov_b32_e32 v76, v10
	v_mov_b32_e32 v77, v10
	v_mov_b32_e32 v78, v10
	v_mov_b32_e32 v79, v10
	v_mov_b32_e32 v80, v10
	v_mov_b32_e32 v81, v10
	v_mov_b32_e32 v82, v10
	v_mov_b32_e32 v83, v10
	v_mov_b32_e32 v84, v10
	v_mov_b32_e32 v85, v10
	v_mov_b32_e32 v86, v10
	v_mov_b32_e32 v87, v10
	v_mov_b32_e32 v88, v10
	v_mov_b32_e32 v89, v10
	v_mov_b32_e32 v90, v10
	v_mov_b32_e32 v91, v10
	v_mov_b32_e32 v92, v10
	v_mov_b32_e32 v93, v10
	v_mov_b32_e32 v94, v10
	v_mov_b32_e32 v95, v10
	v_mov_b32_e32 v96, v10
	v_mov_b32_e32 v97, v10
	v_mov_b32_e32 v98, v10
	v_mov_b32_e32 v99, v10
	v_mov_b32_e32 v100, v10
	v_mov_b32_e32 v101, v10
	v_mov_b32_e32 v102, v10
	v_mov_b32_e32 v103, v10
	v_mov_b32_e32 v104, v10
	v_mov_b32_e32 v105, v10
	v_mov_b32_e32 v106, v10
	v_mov_b32_e32 v107, v10
	v_mov_b32_e32 v108, v10
	v_mov_b32_e32 v109, v10
	v_mov_b32_e32 v110, v10
	v_mov_b32_e32 v111, v10
	v_mov_b32_e32 v112, v10
	v_mov_b32_e32 v113, v10
	v_mov_b32_e32 v114, v10
	v_mov_b32_e32 v115, v10
	v_mov_b32_e32 v116, v10
	v_mov_b32_e32 v117, v10
	v_mov_b32_e32 v118, v10
	v_mov_b32_e32 v119, v10
	v_mov_b32_e32 v120, v10
	v_mov_b32_e32 v121, v10
	v_mov_b32_e32 v122, v10
	v_mov_b32_e32 v123, v10
	v_mov_b32_e32 v124, v10
	v_mov_b32_e32 v125, v10
	v_mov_b32_e32 v126, v10
	v_mov_b32_e32 v127, v10
	v_mov_b32_e32 v128, v10
	v_mov_b32_e32 v129, v10
	s_branch .Lh1_116
; DI f32x4 mfma16(bf16x8 a, bf16x8 b, f32x4 c) { return __builtin_amdgcn_mfma_f32_16x16x32_bf16(a, b, c, 0, 0, 0); }
; template <bool VT>
; DI void gemm_kslab(f32x4 (&acc)[8][4], const u16* sA, const u16* sB, int wm, int wn, int fr, int fq) {
; #pragma unroll
;   for (int ks = 0; ks < 2; ++ks) {
;     bf16x8 tb[4], ta[8];
; #pragma unroll
;     for (int j = 0; j < 4; ++j) tb[j] = ldsv(sB + (wn * 64 + 16 * j + fr) * GSTR + ks * 32 + 8 * fq);
; #pragma unroll
;     for (int i = 0; i < 8; ++i) ta[i] = ldsv(sA + (wm * 128 + 16 * i + fr) * GSTR + ks * 32 + 8 * fq);
; #pragma unroll
;     for (int i = 0; i < 8; ++i)
; #pragma unroll
;       for (int j = 0; j < 4; ++j)
;         acc[i][j] = VT ? mfma16(ta[i], tb[j], acc[i][j]) : mfma16(tb[j], ta[i], acc[i][j]);
;   }
; template <bool VT>
; DI void gemm_mainloop(f32x4 (&acc)[8][4], const char* abase, const char* bbase, unsigned toff, u16* sA, u16* sB, int loff, int wm, int wn, int fr, int fq) {
;     ...
; #pragma unroll 1
;   for (int kt = 0; kt < 16; ++kt) {
;     __syncthreads();
; #pragma unroll
;     for (int i = 0; i < 8; ++i) *(u32x4*)(sA + loff + i * 32 * GSTR) = ra[i];
; #pragma unroll
;     for (int i = 0; i < 4; ++i) *(u32x4*)(sB + loff + i * 32 * GSTR) = rb[i];
;     __syncthreads();
;     if (kt + 1 < 16) {
;       const int ko = (kt + 1) * 128;
; #pragma unroll
;       for (int i = 0; i < 8; ++i) ra[i] = __builtin_amdgcn_raw_buffer_load_b128(ra_rs, (int)toff, i * 65536 + ko, 0);
; #pragma unroll
;       for (int i = 0; i < 4; ++i) rb[i] = __builtin_amdgcn_raw_buffer_load_b128(rb_rs, (int)toff, i * 65536 + ko, 0);
;     }
.Lh1_115:
	s_setprio 1
	ds_read_b128 v[202:205], v184 offset:40960
	ds_read_b128 v[206:209], v184 offset:43520
	ds_read_b128 v[214:217], v184 offset:46080
	ds_read_b128 v[218:221], v184 offset:48640
	ds_read_b128 v[210:213], v185 offset:10240
	ds_read_b128 v[222:225], v185 offset:12800
	s_waitcnt lgkmcnt(1)
	v_mfma_f32_16x16x32_bf16 v[62:65], v[202:205], v[210:213], v[62:65]
	v_mfma_f32_16x16x32_bf16 v[58:61], v[206:209], v[210:213], v[58:61]
	v_mfma_f32_16x16x32_bf16 v[54:57], v[214:217], v[210:213], v[54:57]
	v_mfma_f32_16x16x32_bf16 v[50:53], v[218:221], v[210:213], v[50:53]
	ds_read_b128 v[210:213], v185 offset:15360
	s_waitcnt lgkmcnt(1)
	v_mfma_f32_16x16x32_bf16 v[46:49], v[202:205], v[222:225], v[46:49]
	v_mfma_f32_16x16x32_bf16 v[42:45], v[206:209], v[222:225], v[42:45]
	v_mfma_f32_16x16x32_bf16 v[38:41], v[214:217], v[222:225], v[38:41]
	v_mfma_f32_16x16x32_bf16 v[34:37], v[218:221], v[222:225], v[34:37]
	ds_read_b128 v[222:225], v185 offset:17920
	ds_read_b128 v[226:229], v184 offset:41024
	ds_read_b128 v[230:233], v184 offset:43584
	ds_read_b128 v[234:237], v184 offset:46144
	ds_read_b128 v[238:241], v184 offset:48704
	ds_read_b128 v[242:245], v185 offset:10304
	ds_read_b128 v[246:249], v185 offset:12864
	s_waitcnt lgkmcnt(7)
	v_mfma_f32_16x16x32_bf16 v[30:33], v[202:205], v[210:213], v[30:33]
	v_mfma_f32_16x16x32_bf16 v[26:29], v[206:209], v[210:213], v[26:29]
	v_mfma_f32_16x16x32_bf16 v[22:25], v[214:217], v[210:213], v[22:25]
	v_mfma_f32_16x16x32_bf16 v[18:21], v[218:221], v[210:213], v[18:21]
	s_waitcnt lgkmcnt(6)
	v_mfma_f32_16x16x32_bf16 v[14:17], v[202:205], v[222:225], v[14:17]
	v_mfma_f32_16x16x32_bf16 v[6:9], v[206:209], v[222:225], v[6:9]
	v_mfma_f32_16x16x32_bf16 v[2:5], v[214:217], v[222:225], v[2:5]
	v_mfma_f32_16x16x32_bf16 v[10:13], v[218:221], v[222:225], v[10:13]
	s_waitcnt lgkmcnt(1)
	v_mfma_f32_16x16x32_bf16 v[62:65], v[226:229], v[242:245], v[62:65]
	v_mfma_f32_16x16x32_bf16 v[58:61], v[230:233], v[242:245], v[58:61]
	v_mfma_f32_16x16x32_bf16 v[54:57], v[234:237], v[242:245], v[54:57]
	v_mfma_f32_16x16x32_bf16 v[50:53], v[238:241], v[242:245], v[50:53]
	ds_read_b128 v[202:205], v185 offset:15424
	s_waitcnt lgkmcnt(1)
	v_mfma_f32_16x16x32_bf16 v[46:49], v[226:229], v[246:249], v[46:49]
	v_mfma_f32_16x16x32_bf16 v[42:45], v[230:233], v[246:249], v[42:45]
	v_mfma_f32_16x16x32_bf16 v[38:41], v[234:237], v[246:249], v[38:41]
	v_mfma_f32_16x16x32_bf16 v[34:37], v[238:241], v[246:249], v[34:37]
	ds_read_b128 v[206:209], v185 offset:17984
	s_waitcnt lgkmcnt(1)
	v_mfma_f32_16x16x32_bf16 v[30:33], v[226:229], v[202:205], v[30:33]
	v_mfma_f32_16x16x32_bf16 v[26:29], v[230:233], v[202:205], v[26:29]
	v_mfma_f32_16x16x32_bf16 v[22:25], v[234:237], v[202:205], v[22:25]
	v_mfma_f32_16x16x32_bf16 v[18:21], v[238:241], v[202:205], v[18:21]
	s_waitcnt lgkmcnt(0)
	v_mfma_f32_16x16x32_bf16 v[14:17], v[226:229], v[206:209], v[14:17]
	v_mfma_f32_16x16x32_bf16 v[6:9], v[230:233], v[206:209], v[6:9]
	v_mfma_f32_16x16x32_bf16 v[2:5], v[234:237], v[206:209], v[2:5]
	v_mfma_f32_16x16x32_bf16 v[10:13], v[238:241], v[206:209], v[10:13]
	s_setprio 0
	s_addk_i32 s6, 0x80
	s_cmp_lg_u32 s6, 0x70880
	s_cbranch_scc0 .LBB0_118
.Lh1_116:
	s_cmp_eq_u32 s6, 0x70800
	s_barrier
	s_waitcnt vmcnt(7)
	ds_write_b128 v180, v[134:137] offset:10240
	s_waitcnt vmcnt(6)
	ds_write_b128 v180, v[142:145] offset:15360
	s_waitcnt vmcnt(5)
	ds_write_b128 v180, v[154:157] offset:30720
	s_waitcnt vmcnt(4)
	ds_write_b128 v180, v[158:161] offset:35840
	s_waitcnt vmcnt(3)
	ds_write_b128 v180, v[162:165] offset:40960
	s_waitcnt vmcnt(2)
	ds_write_b128 v180, v[170:173] offset:46080
	s_waitcnt vmcnt(1)
	ds_write_b128 v180, v[166:169] offset:51200
	s_waitcnt vmcnt(0)
	ds_write_b128 v180, v[174:177] offset:56320
	s_waitcnt lgkmcnt(0)
	s_barrier
	s_cbranch_scc1 .Lh1_115
	s_add_i32 s7, s6, 0xfff90000
	s_add_i32 s36, s6, 0xfffa0000
	s_add_i32 s37, s6, 0xfffb0000
	s_add_i32 s38, s6, 0xfffc0000
	s_mov_b32 s87, s67
	buffer_load_dwordx4 v[134:137], v0, s[64:67], s37 offen
	buffer_load_dwordx4 v[142:145], v0, s[64:67], s38 offen
	s_add_i32 s39, s6, 0xffff0000
	buffer_load_dwordx4 v[154:157], v0, s[64:67], s39 offen
	buffer_load_dwordx4 v[158:161], v0, s[64:67], s6 offen
	buffer_load_dwordx4 v[162:165], v0, s[84:87], s7 offen
	buffer_load_dwordx4 v[170:173], v0, s[84:87], s36 offen
	buffer_load_dwordx4 v[166:169], v0, s[84:87], s37 offen
	buffer_load_dwordx4 v[174:177], v0, s[84:87], s38 offen
	s_branch .Lh1_115

; template <int EPI>
; DI void gemm_tile(const Params& p, int layer, int mt, int nt, u16* sm, int wv) {
;     ...
;   if (EPI == 0) {
;     const float* ssl = p.ss + (size_t)layer * MTOK;
;     __syncthreads();
;     u16* stg = sm + (wm * 2 + wn) * (128 * LSTR);
;     if (!vtile) {
;       const float qsc = (nt < 2) ? 0.17677669529663687f * LOG2E
;                         : ((nt >= 8 && nt < 12) || nt == 18 || nt == 19) ? 0.125f * LOG2E : 1.f;
; #pragma unroll
;       for (int i = 0; i < 8; ++i) {
;         const int m = m0 + wm * 128 + 16 * i + fr;
;         const float rs = __builtin_amdgcn_rsqf(ssl[m] * (1.f / DM) + EPS) * qsc;
;         u16* d = stg + (16 * i + fr) * LSTR + 4 * fq;
; #pragma unroll
;         for (int j = 0; j < 4; ++j) {
;           u32x2 v = {pk2(acc[i][j][0] * rs, acc[i][j][1] * rs), pk2(acc[i][j][2] * rs, acc[i][j][3] * rs)};
;           *(u32x2*)(d + 16 * j) = v;
;         }
;       }
.LBB0_124:
	s_waitcnt vmcnt(8)
	v_mbcnt_lo_u32_b32 v138, -1, 0
	v_mbcnt_hi_u32_b32 v138, -1, v138
	s_lshl_b32 s21, s21, 8
	v_add_u32_e32 v0, s33, v138
	v_bfe_u32 v130, v0, 6, 21
	s_waitcnt vmcnt(7)
	v_mul_u32_u24_e32 v135, 0x4800, v130
	v_and_b32_e32 v130, 0xffffff80, v0
	v_and_b32_e32 v137, 15, v138
	v_bfe_u32 v134, v138, 4, 2
	v_bfe_u32 v131, v0, 6, 1
	s_mov_b64 s[6:7], -1
	s_andn2_b64 vcc, exec, s[4:5]
	v_add_u32_e32 v139, s21, v130
	v_lshlrev_b32_e32 v136, 4, v138
	s_barrier
	s_cbranch_vccnz .LBB0_126
	v_or_b32_e32 v132, v139, v137
	v_ashrrev_i32_e32 v133, 31, v132
	v_lshl_add_u64 v[132:133], v[132:133], 2, s[0:1]
	global_load_dword v142, v[132:133], off
	s_and_b32 s4, s20, 0x7ffffffc
	s_cmp_eq_u32 s4, 8
	s_cselect_b64 s[4:5], -1, 0
	s_and_b32 s6, s18, -16
	s_cmpk_eq_i32 s6, 0x90
	s_cselect_b64 s[6:7], -1, 0
	s_or_b64 vcc, s[6:7], s[4:5]
	s_cmp_gt_i32 s20, 1
	v_cndmask_b32_e32 v0, 1.0, v191, vcc
	s_cselect_b64 vcc, -1, 0
	v_cndmask_b32_e32 v0, v192, v0, vcc
	s_waitcnt vmcnt(7)
	v_mul_u32_u24_e32 v143, 0x90, v137
	v_lshlrev_b32_e32 v141, 3, v134
	v_add3_u32 v141, v135, v141, v143
	v_and_b32_e32 v140, 63, v138
	s_mov_b64 s[6:7], 0
	s_waitcnt vmcnt(0)
	v_fmamk_f32 v142, v142, 0x3a800000, v188
	v_rsq_f32_e32 v142, v142
	s_nop 0
	v_mul_f32_e32 v142, v0, v142
	v_pk_mul_f32 v[144:145], v[126:127], v[142:143] op_sel_hi:[1,0]
	v_pk_mul_f32 v[146:147], v[128:129], v[142:143] op_sel_hi:[1,0]
	v_cvt_pk_bf16_f32 v144, v144, v145
	v_cvt_pk_bf16_f32 v145, v146, v147
	v_pk_mul_f32 v[146:147], v[122:123], v[142:143] op_sel_hi:[1,0]
	v_pk_mul_f32 v[148:149], v[124:125], v[142:143] op_sel_hi:[1,0]
	v_cvt_pk_bf16_f32 v146, v146, v147
	v_cvt_pk_bf16_f32 v147, v148, v149
	ds_write2_b64 v141, v[144:145], v[146:147] offset1:4
	v_pk_mul_f32 v[144:145], v[118:119], v[142:143] op_sel_hi:[1,0]
	v_pk_mul_f32 v[146:147], v[120:121], v[142:143] op_sel_hi:[1,0]
	v_cvt_pk_bf16_f32 v144, v144, v145
	v_cvt_pk_bf16_f32 v145, v146, v147
	v_pk_mul_f32 v[146:147], v[114:115], v[142:143] op_sel_hi:[1,0]
	v_pk_mul_f32 v[142:143], v[116:117], v[142:143] op_sel_hi:[1,0]
	v_cvt_pk_bf16_f32 v146, v146, v147
	v_cvt_pk_bf16_f32 v147, v142, v143
	global_load_dword v142, v[132:133], off offset:64
	ds_write2_b64 v141, v[144:145], v[146:147] offset0:8 offset1:12
	s_waitcnt vmcnt(0)
	v_fmamk_f32 v142, v142, 0x3a800000, v188
	v_rsq_f32_e32 v142, v142
	s_nop 0
	v_mul_f32_e32 v142, v0, v142
	v_pk_mul_f32 v[144:145], v[110:111], v[142:143] op_sel_hi:[1,0]
	v_pk_mul_f32 v[146:147], v[112:113], v[142:143] op_sel_hi:[1,0]
	v_cvt_pk_bf16_f32 v144, v144, v145
	v_cvt_pk_bf16_f32 v145, v146, v147
	v_pk_mul_f32 v[146:147], v[106:107], v[142:143] op_sel_hi:[1,0]
	v_pk_mul_f32 v[148:149], v[108:109], v[142:143] op_sel_hi:[1,0]
	v_cvt_pk_bf16_f32 v146, v146, v147
	v_cvt_pk_bf16_f32 v147, v148, v149
	v_add_u32_e32 v148, 0x800, v141
	ds_write2_b64 v148, v[144:145], v[146:147] offset0:32 offset1:36
	v_pk_mul_f32 v[144:145], v[102:103], v[142:143] op_sel_hi:[1,0]
	v_pk_mul_f32 v[146:147], v[104:105], v[142:143] op_sel_hi:[1,0]
	v_cvt_pk_bf16_f32 v144, v144, v145
	v_cvt_pk_bf16_f32 v145, v146, v147
	v_pk_mul_f32 v[146:147], v[98:99], v[142:143] op_sel_hi:[1,0]
	v_pk_mul_f32 v[142:143], v[100:101], v[142:143] op_sel_hi:[1,0]
	v_cvt_pk_bf16_f32 v146, v146, v147
	v_cvt_pk_bf16_f32 v147, v142, v143
	global_load_dword v142, v[132:133], off offset:128
	ds_write2_b64 v148, v[144:145], v[146:147] offset0:40 offset1:44
	s_waitcnt vmcnt(0)
	v_fmamk_f32 v142, v142, 0x3a800000, v188
	v_rsq_f32_e32 v142, v142
	s_nop 0
	v_mul_f32_e32 v142, v0, v142
	v_pk_mul_f32 v[144:145], v[94:95], v[142:143] op_sel_hi:[1,0]
	v_pk_mul_f32 v[146:147], v[96:97], v[142:143] op_sel_hi:[1,0]
	v_cvt_pk_bf16_f32 v144, v144, v145
	v_cvt_pk_bf16_f32 v145, v146, v147
	v_pk_mul_f32 v[146:147], v[90:91], v[142:143] op_sel_hi:[1,0]
	v_pk_mul_f32 v[148:149], v[92:93], v[142:143] op_sel_hi:[1,0]
	v_cvt_pk_bf16_f32 v146, v146, v147
	v_cvt_pk_bf16_f32 v147, v148, v149
	v_add_u32_e32 v148, 0x1000, v141
	ds_write2_b64 v148, v[144:145], v[146:147] offset0:64 offset1:68
	v_pk_mul_f32 v[144:145], v[86:87], v[142:143] op_sel_hi:[1,0]
	v_pk_mul_f32 v[146:147], v[88:89], v[142:143] op_sel_hi:[1,0]
	v_cvt_pk_bf16_f32 v144, v144, v145
	v_cvt_pk_bf16_f32 v145, v146, v147
	v_pk_mul_f32 v[146:147], v[82:83], v[142:143] op_sel_hi:[1,0]
	v_pk_mul_f32 v[142:143], v[84:85], v[142:143] op_sel_hi:[1,0]
	v_cvt_pk_bf16_f32 v146, v146, v147
	v_cvt_pk_bf16_f32 v147, v142, v143
	global_load_dword v142, v[132:133], off offset:192
	ds_write2_b64 v148, v[144:145], v[146:147] offset0:72 offset1:76
	s_waitcnt vmcnt(0)
	v_fmamk_f32 v142, v142, 0x3a800000, v188
	v_rsq_f32_e32 v142, v142
	s_nop 0
	v_mul_f32_e32 v142, v0, v142
	v_pk_mul_f32 v[144:145], v[78:79], v[142:143] op_sel_hi:[1,0]
	v_pk_mul_f32 v[146:147], v[80:81], v[142:143] op_sel_hi:[1,0]
	v_cvt_pk_bf16_f32 v144, v144, v145
	v_cvt_pk_bf16_f32 v145, v146, v147
	v_pk_mul_f32 v[146:147], v[74:75], v[142:143] op_sel_hi:[1,0]
	v_pk_mul_f32 v[148:149], v[76:77], v[142:143] op_sel_hi:[1,0]
	v_cvt_pk_bf16_f32 v146, v146, v147
	v_cvt_pk_bf16_f32 v147, v148, v149
	v_add_u32_e32 v148, 0x1800, v141
	ds_write2_b64 v148, v[144:145], v[146:147] offset0:96 offset1:100
	v_pk_mul_f32 v[144:145], v[70:71], v[142:143] op_sel_hi:[1,0]
	v_pk_mul_f32 v[146:147], v[72:73], v[142:143] op_sel_hi:[1,0]
	v_cvt_pk_bf16_f32 v144, v144, v145
	v_cvt_pk_bf16_f32 v145, v146, v147
	v_pk_mul_f32 v[146:147], v[66:67], v[142:143] op_sel_hi:[1,0]
	v_pk_mul_f32 v[142:143], v[68:69], v[142:143] op_sel_hi:[1,0]
	v_cvt_pk_bf16_f32 v146, v146, v147
	v_cvt_pk_bf16_f32 v147, v142, v143
	global_load_dword v142, v[132:133], off offset:256
	ds_write2_b64 v148, v[144:145], v[146:147] offset0:104 offset1:108
	s_waitcnt vmcnt(0)
; template <int EPI>
; DI void gemm_tile(const Params& p, int layer, int mt, int nt, u16* sm, int wv) {
;     ...
;       for (int i = 0; i < 8; ++i) {
;         const int m = m0 + wm * 128 + 16 * i + fr;
;         const float rs = __builtin_amdgcn_rsqf(ssl[m] * (1.f / DM) + EPS) * qsc;
;         u16* d = stg + (16 * i + fr) * LSTR + 4 * fq;
; #pragma unroll
;         for (int j = 0; j < 4; ++j) {
;           u32x2 v = {pk2(acc[i][j][0] * rs, acc[i][j][1] * rs), pk2(acc[i][j][2] * rs, acc[i][j][3] * rs)};
;           *(u32x2*)(d + 16 * j) = v;
;         }
;       }
;       u16* gdst = p.proj + (size_t)(m0 + wm * 128) * DIN + n0 + wn * 64;
; #pragma unroll
;       for (int t = 0; t < 16; ++t) {
;         const int c = lane + 64 * t, row = c >> 3, kc = c & 7;
;         const u32x4 v = *(const u32x4*)(stg + row * LSTR + kc * 8);
;         *(u32x4*)(gdst + (size_t)row * DIN + kc * 8) = v;
;       }
	v_fmamk_f32 v142, v142, 0x3a800000, v188
	v_rsq_f32_e32 v142, v142
	s_nop 0
	v_mul_f32_e32 v142, v0, v142
	v_pk_mul_f32 v[144:145], v[62:63], v[142:143] op_sel_hi:[1,0]
	v_pk_mul_f32 v[146:147], v[64:65], v[142:143] op_sel_hi:[1,0]
	v_cvt_pk_bf16_f32 v144, v144, v145
	v_cvt_pk_bf16_f32 v145, v146, v147
	v_pk_mul_f32 v[146:147], v[58:59], v[142:143] op_sel_hi:[1,0]
	v_pk_mul_f32 v[148:149], v[60:61], v[142:143] op_sel_hi:[1,0]
	v_cvt_pk_bf16_f32 v146, v146, v147
	v_cvt_pk_bf16_f32 v147, v148, v149
	v_add_u32_e32 v148, 0x2000, v141
	ds_write2_b64 v148, v[144:145], v[146:147] offset0:128 offset1:132
	v_pk_mul_f32 v[144:145], v[54:55], v[142:143] op_sel_hi:[1,0]
	v_pk_mul_f32 v[146:147], v[56:57], v[142:143] op_sel_hi:[1,0]
	v_cvt_pk_bf16_f32 v144, v144, v145
	v_cvt_pk_bf16_f32 v145, v146, v147
	v_pk_mul_f32 v[146:147], v[50:51], v[142:143] op_sel_hi:[1,0]
	v_pk_mul_f32 v[142:143], v[52:53], v[142:143] op_sel_hi:[1,0]
	v_cvt_pk_bf16_f32 v146, v146, v147
	v_cvt_pk_bf16_f32 v147, v142, v143
	global_load_dword v142, v[132:133], off offset:320
	ds_write2_b64 v148, v[144:145], v[146:147] offset0:136 offset1:140
	s_waitcnt vmcnt(0)
	v_fmamk_f32 v142, v142, 0x3a800000, v188
	v_rsq_f32_e32 v142, v142
	s_nop 0
	v_mul_f32_e32 v142, v0, v142
	v_pk_mul_f32 v[144:145], v[46:47], v[142:143] op_sel_hi:[1,0]
	v_pk_mul_f32 v[146:147], v[48:49], v[142:143] op_sel_hi:[1,0]
	v_cvt_pk_bf16_f32 v144, v144, v145
	v_cvt_pk_bf16_f32 v145, v146, v147
	v_pk_mul_f32 v[146:147], v[42:43], v[142:143] op_sel_hi:[1,0]
	v_pk_mul_f32 v[148:149], v[44:45], v[142:143] op_sel_hi:[1,0]
	v_cvt_pk_bf16_f32 v146, v146, v147
	v_cvt_pk_bf16_f32 v147, v148, v149
	v_add_u32_e32 v148, 0x2800, v141
	ds_write2_b64 v148, v[144:145], v[146:147] offset0:160 offset1:164
	v_pk_mul_f32 v[144:145], v[38:39], v[142:143] op_sel_hi:[1,0]
	v_pk_mul_f32 v[146:147], v[40:41], v[142:143] op_sel_hi:[1,0]
	v_cvt_pk_bf16_f32 v144, v144, v145
	v_cvt_pk_bf16_f32 v145, v146, v147
	v_pk_mul_f32 v[146:147], v[34:35], v[142:143] op_sel_hi:[1,0]
	v_pk_mul_f32 v[142:143], v[36:37], v[142:143] op_sel_hi:[1,0]
	v_cvt_pk_bf16_f32 v146, v146, v147
	v_cvt_pk_bf16_f32 v147, v142, v143
	global_load_dword v142, v[132:133], off offset:384
	ds_write2_b64 v148, v[144:145], v[146:147] offset0:168 offset1:172
	global_load_dword v132, v[132:133], off offset:448
	s_waitcnt vmcnt(1)
	v_fmamk_f32 v142, v142, 0x3a800000, v188
	v_rsq_f32_e32 v142, v142
	s_waitcnt vmcnt(0)
	v_fmamk_f32 v132, v132, 0x3a800000, v188
	v_rsq_f32_e32 v132, v132
	v_mul_f32_e32 v142, v0, v142
	v_pk_mul_f32 v[144:145], v[30:31], v[142:143] op_sel_hi:[1,0]
	v_pk_mul_f32 v[146:147], v[32:33], v[142:143] op_sel_hi:[1,0]
	v_cvt_pk_bf16_f32 v144, v144, v145
	v_cvt_pk_bf16_f32 v145, v146, v147
	v_pk_mul_f32 v[146:147], v[26:27], v[142:143] op_sel_hi:[1,0]
	v_pk_mul_f32 v[148:149], v[28:29], v[142:143] op_sel_hi:[1,0]
	v_cvt_pk_bf16_f32 v146, v146, v147
	v_cvt_pk_bf16_f32 v147, v148, v149
	v_add_u32_e32 v148, 0x3000, v141
	ds_write2_b64 v148, v[144:145], v[146:147] offset0:192 offset1:196
	v_pk_mul_f32 v[144:145], v[22:23], v[142:143] op_sel_hi:[1,0]
	v_pk_mul_f32 v[146:147], v[24:25], v[142:143] op_sel_hi:[1,0]
	v_cvt_pk_bf16_f32 v144, v144, v145
	v_cvt_pk_bf16_f32 v145, v146, v147
	v_pk_mul_f32 v[146:147], v[18:19], v[142:143] op_sel_hi:[1,0]
	v_pk_mul_f32 v[142:143], v[20:21], v[142:143] op_sel_hi:[1,0]
	v_mul_f32_e32 v0, v0, v132
	v_cvt_pk_bf16_f32 v146, v146, v147
	v_cvt_pk_bf16_f32 v147, v142, v143
	v_pk_mul_f32 v[132:133], v[14:15], v[0:1] op_sel_hi:[1,0]
	v_pk_mul_f32 v[142:143], v[16:17], v[0:1] op_sel_hi:[1,0]
	ds_write2_b64 v148, v[144:145], v[146:147] offset0:200 offset1:204
	v_cvt_pk_bf16_f32 v132, v132, v133
	v_cvt_pk_bf16_f32 v133, v142, v143
	v_pk_mul_f32 v[142:143], v[6:7], v[0:1] op_sel_hi:[1,0]
	v_pk_mul_f32 v[144:145], v[8:9], v[0:1] op_sel_hi:[1,0]
	v_cvt_pk_bf16_f32 v142, v142, v143
	v_cvt_pk_bf16_f32 v143, v144, v145
	v_add_u32_e32 v141, 0x3800, v141
	ds_write2_b64 v141, v[132:133], v[142:143] offset0:224 offset1:228
	v_pk_mul_f32 v[132:133], v[2:3], v[0:1] op_sel_hi:[1,0]
	v_pk_mul_f32 v[142:143], v[4:5], v[0:1] op_sel_hi:[1,0]
	v_cvt_pk_bf16_f32 v132, v132, v133
	v_cvt_pk_bf16_f32 v133, v142, v143
	v_pk_mul_f32 v[142:143], v[10:11], v[0:1] op_sel_hi:[1,0]
	v_pk_mul_f32 v[144:145], v[12:13], v[0:1] op_sel_hi:[1,0]
	v_cvt_pk_bf16_f32 v142, v142, v143
	v_cvt_pk_bf16_f32 v143, v144, v145
	ds_write2_b64 v141, v[132:133], v[142:143] offset0:232 offset1:236
	v_mov_b64_e32 v[132:133], s[62:63]
	v_mad_i64_i32 v[132:133], s[4:5], v139, s8, v[132:133]
	v_lshl_add_u64 v[132:133], s[2:3], 1, v[132:133]
	v_lshlrev_b32_e32 v0, 7, v131
	v_lshrrev_b32_e32 v148, 3, v140
	v_lshl_add_u64 v[132:133], v[132:133], 0, v[0:1]
	v_and_b32_e32 v0, 0x70, v136
	v_mul_u32_u24_e32 v140, 0x90, v148
	v_add3_u32 v149, v135, v0, v140
	ds_read_b128 v[140:143], v149
	v_lshl_add_u64 v[132:133], v[132:133], 0, v[0:1]
	v_mul_u32_u24_e32 v0, 0xd00, v148
	v_lshlrev_b32_e32 v0, 1, v0
	v_lshl_add_u64 v[144:145], v[132:133], 0, v[0:1]
	s_cmp_eq_u32 s40, 2
	s_cbranch_scc1 .Lepi_hi_skip
	s_waitcnt lgkmcnt(0)
	global_store_dwordx4 v[144:145], v[140:143], off
	ds_read_b128 v[140:143], v149 offset:1152
	s_mov_b32 s2, 0xd000
	v_add_co_u32_e32 v146, vcc, s2, v144
	s_mov_b32 s2, 0x1a000
	s_nop 0
	v_addc_co_u32_e32 v147, vcc, 0, v145, vcc
	s_waitcnt lgkmcnt(0)
	global_store_dwordx4 v[146:147], v[140:143], off
	ds_read_b128 v[140:143], v149 offset:2304
	v_add_co_u32_e32 v146, vcc, s2, v144
	s_mov_b32 s2, 0x27000
	s_nop 0
	v_addc_co_u32_e32 v147, vcc, 0, v145, vcc
	s_waitcnt lgkmcnt(0)
	global_store_dwordx4 v[146:147], v[140:143], off
	ds_read_b128 v[140:143], v149 offset:3456
	v_add_co_u32_e32 v144, vcc, s2, v144
	s_movk_i32 s2, 0xd00
	s_nop 0
	v_addc_co_u32_e32 v145, vcc, 0, v145, vcc
	s_waitcnt lgkmcnt(0)
	global_store_dwordx4 v[144:145], v[140:143], off
	ds_read_b128 v[140:143], v149 offset:4608
	v_add_u32_e32 v144, 0x34000, v0
	v_mov_b32_e32 v145, v1
	v_lshl_add_u64 v[144:145], v[132:133], 0, v[144:145]
	s_waitcnt lgkmcnt(0)
	global_store_dwordx4 v[144:145], v[140:143], off
	ds_read_b128 v[140:143], v149 offset:5760
	v_add_u32_e32 v144, 0x41000, v0
	v_mov_b32_e32 v145, v1
	v_lshl_add_u64 v[144:145], v[132:133], 0, v[144:145]
	s_waitcnt lgkmcnt(0)
	global_store_dwordx4 v[144:145], v[140:143], off
	ds_read_b128 v[140:143], v149 offset:6912
	v_add_u32_e32 v144, 0x4e000, v0
	v_mov_b32_e32 v145, v1
	v_lshl_add_u64 v[144:145], v[132:133], 0, v[144:145]
	s_waitcnt lgkmcnt(0)
	global_store_dwordx4 v[144:145], v[140:143], off
	ds_read_b128 v[140:143], v149 offset:8064
	v_add_u32_e32 v144, 0x5b000, v0
	v_mov_b32_e32 v145, v1
	v_lshl_add_u64 v[144:145], v[132:133], 0, v[144:145]
	s_waitcnt lgkmcnt(0)
	global_store_dwordx4 v[144:145], v[140:143], off
	s_cmp_eq_u32 s40, 1
	s_cbranch_scc1 .Lgx_halfdone
	s_branch .Lepi_t8
; template <int EPI>
; DI void gemm_tile(const Params& p, int layer, int mt, int nt, u16* sm, int wv) {
;     ...
;       u16* gdst = p.proj + (size_t)(m0 + wm * 128) * DIN + n0 + wn * 64;
; #pragma unroll
;       for (int t = 0; t < 16; ++t) {
;         const int c = lane + 64 * t, row = c >> 3, kc = c & 7;
;         const u32x4 v = *(const u32x4*)(stg + row * LSTR + kc * 8);
;         *(u32x4*)(gdst + (size_t)row * DIN + kc * 8) = v;
;       }
.Lepi_hi_skip:
	s_movk_i32 s2, 0xd00
.Lepi_t8:
	ds_read_b128 v[140:143], v149 offset:9216
	v_add_u32_e32 v144, 0x68000, v0
	v_mov_b32_e32 v145, v1
	v_lshl_add_u64 v[144:145], v[132:133], 0, v[144:145]
	s_waitcnt lgkmcnt(0)
	global_store_dwordx4 v[144:145], v[140:143], off
	ds_read_b128 v[140:143], v149 offset:10368
	v_add_u32_e32 v144, 0x75000, v0
	v_mov_b32_e32 v145, v1
	v_lshl_add_u64 v[144:145], v[132:133], 0, v[144:145]
	s_waitcnt lgkmcnt(0)
	global_store_dwordx4 v[144:145], v[140:143], off
	ds_read_b128 v[140:143], v149 offset:11520
	v_add_u32_e32 v144, 0x82000, v0
	v_mov_b32_e32 v145, v1
	v_lshl_add_u64 v[144:145], v[132:133], 0, v[144:145]
	s_waitcnt lgkmcnt(0)
	global_store_dwordx4 v[144:145], v[140:143], off
	ds_read_b128 v[140:143], v149 offset:12672
	v_add_u32_e32 v144, 0x8f000, v0
	v_mov_b32_e32 v145, v1
	v_lshl_add_u64 v[144:145], v[132:133], 0, v[144:145]
	s_waitcnt lgkmcnt(0)
	global_store_dwordx4 v[144:145], v[140:143], off
	ds_read_b128 v[140:143], v149 offset:13824
	v_add_u32_e32 v144, 0x9c000, v0
	v_mov_b32_e32 v145, v1
	v_lshl_add_u64 v[144:145], v[132:133], 0, v[144:145]
	s_waitcnt lgkmcnt(0)
	global_store_dwordx4 v[144:145], v[140:143], off
	ds_read_b128 v[140:143], v149 offset:14976
	v_add_u32_e32 v144, 0xa9000, v0
	v_mov_b32_e32 v145, v1
	v_lshl_add_u64 v[144:145], v[132:133], 0, v[144:145]
	v_add_u32_e32 v0, 0xb6000, v0
	s_waitcnt lgkmcnt(0)
	global_store_dwordx4 v[144:145], v[140:143], off
	ds_read_b128 v[140:143], v149 offset:16128
	v_lshl_add_u64 v[144:145], v[132:133], 0, v[0:1]
	v_mad_u32_u24 v0, v148, s2, v193
	s_waitcnt lgkmcnt(0)
	global_store_dwordx4 v[144:145], v[140:143], off
	s_nop 1
	v_add_u32_e32 v140, 0x4380, v149

; __global__ void __launch_bounds__(256, 2) hymba_mega(Params p) {
;     ...
;   for (int layer = 0; layer < DEPTH; ++layer) {
;     for (int rep = 0; rep < REP_G0; ++rep) {
;       for (int u = lb; u < 8 * 26; u += nxb) gemm_tile<0>(p, layer, xcd + 8 * (u & 7), u >> 3, sm, wv);
;       xcd_barrier(gb);
.Lgx_exit:
	s_cmp_lg_u32 s40, 0
	s_cbranch_scc1 .Lgx_halfdone
	s_sub_i32 s2, s18, 0xc0
	s_cmp_lt_u32 s2, 32
	s_cbranch_scc0 .LBB0_141
	s_and_b32 s3, s2, 15
	s_lshr_b32 s40, s2, 4
	s_add_i32 s40, s40, 1
	s_add_i32 s18, s3, 0xc0
	s_branch .LBB0_113
.Lgx_halfdone:
	s_mov_b32 s40, 0
	s_branch .LBB0_141
